# P0: w_out transpose items load their 32 per-row norm scales in one batch instead of a serialized chain
# baseline (speedup 1.0000x reference)
.LBB0_623:
	s_andn2_b64 vcc, exec, s[6:7]
	s_cbranch_vccnz .LBB0_625
	s_load_dwordx4 s[24:27], s[0:1], 0x80
	s_load_dwordx2 s[6:7], s[0:1], 0x90
	s_add_i32 s11, s20, 0xfffffc80
	s_lshl_b64 s[8:9], s[4:5], 22
	v_lshlrev_b32_e32 v0, 2, v6
	s_waitcnt lgkmcnt(0)
	s_add_u32 s21, s6, s8
	s_addc_u32 s23, s7, s9
	s_lshl_b32 s6, s4, 9
	s_ashr_i32 s7, s6, 31
	s_lshl_b64 s[8:9], s[6:7], 2
	s_add_u32 s6, s24, s8
	s_addc_u32 s7, s25, s9
	s_add_u32 s8, s26, s8
	s_addc_u32 s9, s27, s9
	s_and_b32 s5, s14, 0x3e0
	s_and_b32 s10, s16, 0x3c0
	s_lshl_b32 s22, s5, 2
	s_add_u32 s22, s21, s22
	v_or_b32_e32 v36, s10, v7
	s_addc_u32 s23, s23, 0
	v_lshl_add_u64 v[2:3], s[22:23], 0, v[0:1]
	v_lshlrev_b32_e32 v0, 12, v36
	v_lshl_add_u64 v[2:3], v[2:3], 0, v[0:1]
	v_add_co_u32_e32 v4, vcc, s29, v2
	global_load_dword v38, v[2:3], off nt
	s_nop 0
	v_addc_co_u32_e32 v5, vcc, 0, v3, vcc
	global_load_dword v40, v[4:5], off nt
	v_add_co_u32_e32 v4, vcc, s49, v2
	s_mov_b32 s21, 0x20000
	s_nop 0
	v_addc_co_u32_e32 v5, vcc, 0, v3, vcc
	global_load_dword v41, v[4:5], off nt
	v_add_co_u32_e32 v4, vcc, s65, v2
	v_lshlrev_b32_e32 v0, 2, v36
	s_nop 0
	v_addc_co_u32_e32 v5, vcc, 0, v3, vcc
	global_load_dword v42, v[4:5], off nt
	v_add_co_u32_e32 v4, vcc, s31, v2
	s_cmpk_lt_u32 s11, 0x100
	s_nop 0
	v_addc_co_u32_e32 v5, vcc, 0, v3, vcc
	global_load_dword v43, v[4:5], off nt
	v_add_co_u32_e32 v4, vcc, s56, v2
	s_nop 1
	v_addc_co_u32_e32 v5, vcc, 0, v3, vcc
	global_load_dword v44, v[4:5], off nt
	v_add_co_u32_e32 v4, vcc, s90, v2
	s_nop 1
	v_addc_co_u32_e32 v5, vcc, 0, v3, vcc
	global_load_dword v45, v[4:5], off nt
	v_add_co_u32_e32 v4, vcc, s78, v2
	s_nop 1
	v_addc_co_u32_e32 v5, vcc, 0, v3, vcc
	global_load_dword v46, v[4:5], off nt
	v_add_co_u32_e32 v4, vcc, s28, v2
	s_nop 1
	v_addc_co_u32_e32 v5, vcc, 0, v3, vcc
	global_load_dword v47, v[4:5], off nt
	v_add_co_u32_e32 v4, vcc, s54, v2
	s_nop 1
	v_addc_co_u32_e32 v5, vcc, 0, v3, vcc
	global_load_dword v48, v[4:5], off nt
	v_add_co_u32_e32 v4, vcc, s30, v2
	s_nop 1
	v_addc_co_u32_e32 v5, vcc, 0, v3, vcc
	global_load_dword v49, v[4:5], off nt
	v_add_co_u32_e32 v4, vcc, s45, v2
	s_nop 1
	v_addc_co_u32_e32 v5, vcc, 0, v3, vcc
	global_load_dword v50, v[4:5], off nt
	v_add_co_u32_e32 v4, vcc, s95, v2
	s_nop 1
	v_addc_co_u32_e32 v5, vcc, 0, v3, vcc
	global_load_dword v51, v[4:5], off nt
	v_add_co_u32_e32 v4, vcc, s46, v2
	s_nop 1
	v_addc_co_u32_e32 v5, vcc, 0, v3, vcc
	global_load_dword v52, v[4:5], off nt
	v_add_co_u32_e32 v4, vcc, s77, v2
	s_nop 1
	v_addc_co_u32_e32 v5, vcc, 0, v3, vcc
	global_load_dword v53, v[4:5], off nt
	v_add_co_u32_e32 v4, vcc, s64, v2
	s_nop 1
	v_addc_co_u32_e32 v5, vcc, 0, v3, vcc
	global_load_dword v54, v[4:5], off nt
	v_add_co_u32_e32 v4, vcc, s21, v2
	s_mov_b32 s21, 0x22000
	s_nop 0
	v_addc_co_u32_e32 v5, vcc, 0, v3, vcc
	global_load_dword v35, v[4:5], off nt
	v_add_co_u32_e32 v4, vcc, s21, v2
	s_mov_b32 s21, 0x28000
	s_nop 0
	v_addc_co_u32_e32 v5, vcc, 0, v3, vcc
	global_load_dword v34, v[4:5], off nt
	v_add_co_u32_e32 v4, vcc, s97, v2
	s_nop 1
	v_addc_co_u32_e32 v5, vcc, 0, v3, vcc
	global_load_dword v33, v[4:5], off nt
	v_add_co_u32_e32 v4, vcc, s79, v2
	s_nop 1
	v_addc_co_u32_e32 v5, vcc, 0, v3, vcc
	global_load_dword v32, v[4:5], off nt
	v_add_co_u32_e32 v4, vcc, s21, v2
	s_mov_b32 s21, 0x2c000
	s_nop 0
	v_addc_co_u32_e32 v5, vcc, 0, v3, vcc
	global_load_dword v31, v[4:5], off nt
	v_add_co_u32_e32 v4, vcc, s55, v2
	s_nop 1
	v_addc_co_u32_e32 v5, vcc, 0, v3, vcc
	global_load_dword v30, v[4:5], off nt
	v_add_co_u32_e32 v4, vcc, s21, v2
	s_mov_b32 s21, 0x2e000
	s_nop 0
	v_addc_co_u32_e32 v5, vcc, 0, v3, vcc
	global_load_dword v29, v[4:5], off nt
	v_add_co_u32_e32 v4, vcc, s21, v2
	s_mov_b32 s21, 0x32000
	s_nop 0
	v_addc_co_u32_e32 v5, vcc, 0, v3, vcc
	global_load_dword v28, v[4:5], off nt
	v_add_co_u32_e32 v4, vcc, s91, v2
	s_nop 1
	v_addc_co_u32_e32 v5, vcc, 0, v3, vcc
	global_load_dword v17, v[4:5], off nt
	v_add_co_u32_e32 v4, vcc, s21, v2
	s_mov_b32 s21, 0x3a000
	s_nop 0
	v_addc_co_u32_e32 v5, vcc, 0, v3, vcc
	global_load_dword v16, v[4:5], off nt
	v_add_co_u32_e32 v4, vcc, s85, v2
	s_nop 1
	v_addc_co_u32_e32 v5, vcc, 0, v3, vcc
	global_load_dword v15, v[4:5], off nt
	v_add_co_u32_e32 v4, vcc, s94, v2
	s_nop 1
	v_addc_co_u32_e32 v5, vcc, 0, v3, vcc
	global_load_dword v14, v[4:5], off nt
	v_add_co_u32_e32 v4, vcc, s93, v2
	s_nop 1
	v_addc_co_u32_e32 v5, vcc, 0, v3, vcc
	global_load_dword v13, v[4:5], off nt
	v_add_co_u32_e32 v4, vcc, s21, v2
	s_mov_b32 s21, 0x3e000
	s_nop 0
	v_addc_co_u32_e32 v5, vcc, 0, v3, vcc
	global_load_dword v12, v[4:5], off nt
	v_add_co_u32_e32 v4, vcc, s92, v2
	s_nop 1
	v_addc_co_u32_e32 v5, vcc, 0, v3, vcc
	v_add_co_u32_e32 v2, vcc, s21, v2
	global_load_dword v11, v[4:5], off nt
	s_nop 0
	v_addc_co_u32_e32 v3, vcc, 0, v3, vcc
	global_load_dword v10, v[2:3], off nt
	v_lshl_add_u64 v[2:3], s[8:9], 0, v[0:1]
	s_movk_i32 s8, 0xf800
	s_mov_b32 s9, -1
	s_cselect_b64 vcc, -1, 0
	v_lshl_add_u64 v[36:37], v[2:3], 0, s[8:9]
	v_lshl_add_u64 v[4:5], s[6:7], 0, v[0:1]
	s_waitcnt vmcnt(30)
	v_lshl_add_u64 v[96:97], v[2:3], 0, s[8:9]
	v_cndmask_b32_e32 v97, v97, v5, vcc
	v_cndmask_b32_e32 v96, v96, v4, vcc
	global_load_dword v64, v[96:97], off
	global_load_dword v65, v[96:97], off offset:8
	global_load_dword v66, v[96:97], off offset:16
	global_load_dword v67, v[96:97], off offset:24
	global_load_dword v68, v[96:97], off offset:32
	global_load_dword v69, v[96:97], off offset:40
	global_load_dword v70, v[96:97], off offset:48
	global_load_dword v71, v[96:97], off offset:56
	global_load_dword v72, v[96:97], off offset:64
	global_load_dword v73, v[96:97], off offset:72
	global_load_dword v74, v[96:97], off offset:80
	global_load_dword v75, v[96:97], off offset:88
	global_load_dword v76, v[96:97], off offset:96
	global_load_dword v77, v[96:97], off offset:104
	global_load_dword v78, v[96:97], off offset:112
	global_load_dword v79, v[96:97], off offset:120
	global_load_dword v80, v[96:97], off offset:128
	global_load_dword v81, v[96:97], off offset:136
	global_load_dword v82, v[96:97], off offset:144
	global_load_dword v83, v[96:97], off offset:152
	global_load_dword v84, v[96:97], off offset:160
	global_load_dword v85, v[96:97], off offset:168
	global_load_dword v86, v[96:97], off offset:176
	global_load_dword v87, v[96:97], off offset:184
	global_load_dword v88, v[96:97], off offset:192
	global_load_dword v89, v[96:97], off offset:200
	global_load_dword v90, v[96:97], off offset:208
	global_load_dword v91, v[96:97], off offset:216
	global_load_dword v92, v[96:97], off offset:224
	global_load_dword v93, v[96:97], off offset:232
	global_load_dword v94, v[96:97], off offset:240
	global_load_dword v95, v[96:97], off offset:248
	v_cndmask_b32_e32 v37, v37, v5, vcc
	v_cndmask_b32_e32 v36, v36, v4, vcc
	s_nop 0
	s_movk_i32 s6, 0xf808
	s_mov_b32 s7, -1
	v_lshl_add_u64 v[36:37], v[4:5], 0, 8
	s_waitcnt vmcnt(0)
	v_mul_f32_e32 v0, v38, v64
	v_lshl_add_u64 v[38:39], v[2:3], 0, s[6:7]
	s_movk_i32 s6, 0xf810
	v_cndmask_b32_e32 v37, v39, v37, vcc
	v_cndmask_b32_e32 v36, v38, v36, vcc
	s_mov_b32 s7, -1
	ds_write_b32 v9, v0
	s_nop 0
	v_lshl_add_u64 v[36:37], v[4:5], 0, 16
	v_lshl_add_u64 v[38:39], v[2:3], 0, s[6:7]
	v_cndmask_b32_e32 v37, v39, v37, vcc
	v_cndmask_b32_e32 v36, v38, v36, vcc
	s_nop 0
	s_movk_i32 s6, 0xf818
	s_mov_b32 s7, -1
	v_lshl_add_u64 v[38:39], v[2:3], 0, s[6:7]
	s_movk_i32 s6, 0xf820
	s_mov_b32 s7, -1
	s_waitcnt vmcnt(1)
	v_mul_f32_e32 v0, v40, v65
	v_add_u32_e32 v40, 0x400, v27
	s_waitcnt vmcnt(0)
	v_mul_f32_e32 v36, v41, v66
	ds_write2_b32 v27, v0, v36 offset1:66
	v_lshl_add_u64 v[36:37], v[4:5], 0, 24
	v_cndmask_b32_e32 v37, v39, v37, vcc
	v_cndmask_b32_e32 v36, v38, v36, vcc
	s_nop 0
	v_lshl_add_u64 v[36:37], v[4:5], 0, 32
	v_lshl_add_u64 v[38:39], v[2:3], 0, s[6:7]
	v_cndmask_b32_e32 v37, v39, v37, vcc
	v_cndmask_b32_e32 v36, v38, v36, vcc
	s_nop 0
	s_movk_i32 s6, 0xf828
	s_mov_b32 s7, -1
	v_lshl_add_u64 v[38:39], v[2:3], 0, s[6:7]
	s_movk_i32 s6, 0xf830
	s_mov_b32 s7, -1
	s_waitcnt vmcnt(1)
	v_mul_f32_e32 v0, v42, v67
	s_waitcnt vmcnt(0)
	v_mul_f32_e32 v36, v43, v68
	ds_write2_b32 v27, v0, v36 offset0:132 offset1:198
	v_lshl_add_u64 v[36:37], v[4:5], 0, 40
	v_cndmask_b32_e32 v37, v39, v37, vcc
	v_cndmask_b32_e32 v36, v38, v36, vcc
	s_nop 0
	v_lshl_add_u64 v[36:37], v[4:5], 0, 48
	v_lshl_add_u64 v[38:39], v[2:3], 0, s[6:7]
	v_cndmask_b32_e32 v37, v39, v37, vcc
	v_cndmask_b32_e32 v36, v38, v36, vcc
	s_nop 0
	s_movk_i32 s6, 0xf838
	s_mov_b32 s7, -1
	v_lshl_add_u64 v[38:39], v[2:3], 0, s[6:7]
	s_movk_i32 s6, 0xf840
	s_mov_b32 s7, -1
	s_waitcnt vmcnt(1)
	v_mul_f32_e32 v0, v44, v69
	s_waitcnt vmcnt(0)
	v_mul_f32_e32 v36, v45, v70
	ds_write2_b32 v40, v0, v36 offset0:8 offset1:74
	v_lshl_add_u64 v[36:37], v[4:5], 0, 56
	v_cndmask_b32_e32 v37, v39, v37, vcc
	v_cndmask_b32_e32 v36, v38, v36, vcc
	s_nop 0
	v_lshl_add_u64 v[36:37], v[4:5], 0, 64
	v_lshl_add_u64 v[38:39], v[2:3], 0, s[6:7]
	v_cndmask_b32_e32 v37, v39, v37, vcc
	v_cndmask_b32_e32 v36, v38, v36, vcc
	s_nop 0
	s_mov_b64 s[6:7], 0x48
	s_waitcnt vmcnt(1)
	v_mul_f32_e32 v0, v46, v71
	s_waitcnt vmcnt(0)
	v_mul_f32_e32 v36, v47, v72
	ds_write2_b32 v40, v0, v36 offset0:140 offset1:206
	v_lshl_add_u64 v[36:37], v[4:5], 0, s[6:7]
	s_movk_i32 s6, 0xf848
	s_mov_b32 s7, -1
	v_lshl_add_u64 v[38:39], v[2:3], 0, s[6:7]
	v_cndmask_b32_e32 v37, v39, v37, vcc
	v_cndmask_b32_e32 v36, v38, v36, vcc
	s_mov_b64 s[6:7], 0x50
	s_nop 0
	v_lshl_add_u64 v[36:37], v[4:5], 0, s[6:7]
	s_movk_i32 s6, 0xf850
	s_mov_b32 s7, -1
	v_lshl_add_u64 v[38:39], v[2:3], 0, s[6:7]
	v_cndmask_b32_e32 v37, v39, v37, vcc
	v_cndmask_b32_e32 v36, v38, v36, vcc
	s_nop 0
	v_add_u32_e32 v40, 0x800, v27
	s_mov_b64 s[6:7], 0x58
	s_waitcnt vmcnt(1)
	v_mul_f32_e32 v0, v48, v73
	s_waitcnt vmcnt(0)
	v_mul_f32_e32 v36, v49, v74
	ds_write2_b32 v40, v0, v36 offset0:16 offset1:82
	v_lshl_add_u64 v[36:37], v[4:5], 0, s[6:7]
	s_movk_i32 s6, 0xf858
	s_mov_b32 s7, -1
	v_lshl_add_u64 v[38:39], v[2:3], 0, s[6:7]
	v_cndmask_b32_e32 v37, v39, v37, vcc
	v_cndmask_b32_e32 v36, v38, v36, vcc
	s_mov_b64 s[6:7], 0x60
	s_nop 0
	v_lshl_add_u64 v[36:37], v[4:5], 0, s[6:7]
	s_movk_i32 s6, 0xf860
	s_mov_b32 s7, -1
	v_lshl_add_u64 v[38:39], v[2:3], 0, s[6:7]
	v_cndmask_b32_e32 v37, v39, v37, vcc
	v_cndmask_b32_e32 v36, v38, v36, vcc
	s_nop 0
	s_mov_b64 s[6:7], 0x68
	s_waitcnt vmcnt(1)
	v_mul_f32_e32 v0, v50, v75
	s_waitcnt vmcnt(0)
	v_mul_f32_e32 v36, v51, v76
	ds_write2_b32 v40, v0, v36 offset0:148 offset1:214
	v_lshl_add_u64 v[36:37], v[4:5], 0, s[6:7]
	s_movk_i32 s6, 0xf868
	s_mov_b32 s7, -1
	v_lshl_add_u64 v[38:39], v[2:3], 0, s[6:7]
	v_cndmask_b32_e32 v37, v39, v37, vcc
	v_cndmask_b32_e32 v36, v38, v36, vcc
	s_mov_b64 s[6:7], 0x70
	s_nop 0
	v_lshl_add_u64 v[36:37], v[4:5], 0, s[6:7]
	s_movk_i32 s6, 0xf870
	s_mov_b32 s7, -1
	v_lshl_add_u64 v[38:39], v[2:3], 0, s[6:7]
	v_cndmask_b32_e32 v37, v39, v37, vcc
	v_cndmask_b32_e32 v36, v38, v36, vcc
	s_nop 0
	v_add_u32_e32 v40, 0xc00, v27
	s_mov_b64 s[6:7], 0x78
	s_waitcnt vmcnt(1)
	v_mul_f32_e32 v0, v52, v77
	s_waitcnt vmcnt(0)
	v_mul_f32_e32 v36, v53, v78
	ds_write2_b32 v40, v0, v36 offset0:24 offset1:90
	v_lshl_add_u64 v[36:37], v[4:5], 0, s[6:7]
	s_movk_i32 s6, 0xf878
	s_mov_b32 s7, -1
	v_lshl_add_u64 v[38:39], v[2:3], 0, s[6:7]
	s_movk_i32 s6, 0xf880
	v_cndmask_b32_e32 v37, v39, v37, vcc
	v_cndmask_b32_e32 v36, v38, v36, vcc
	s_mov_b32 s7, -1
	s_nop 0
	v_lshl_add_u64 v[36:37], v[4:5], 0, s[86:87]
	v_lshl_add_u64 v[38:39], v[2:3], 0, s[6:7]
	v_cndmask_b32_e32 v37, v39, v37, vcc
	v_cndmask_b32_e32 v36, v38, v36, vcc
	s_nop 0
	s_mov_b64 s[6:7], 0x88
	s_waitcnt vmcnt(1)
	v_mul_f32_e32 v0, v54, v79
	s_waitcnt vmcnt(0)
	v_mul_f32_e32 v35, v35, v80
	v_lshl_add_u64 v[36:37], v[4:5], 0, s[6:7]
	s_movk_i32 s6, 0xf888
	s_mov_b32 s7, -1
	v_lshl_add_u64 v[38:39], v[2:3], 0, s[6:7]
	v_cndmask_b32_e32 v37, v39, v37, vcc
	v_cndmask_b32_e32 v36, v38, v36, vcc
	ds_write2_b32 v40, v0, v35 offset0:156 offset1:222
	s_nop 0
	s_mov_b64 s[6:7], 0x90
	v_add_u32_e32 v38, 0x1000, v27
	s_waitcnt vmcnt(0)
	v_mul_f32_e32 v0, v34, v81
	v_lshl_add_u64 v[34:35], v[4:5], 0, s[6:7]
	s_movk_i32 s6, 0xf890
	s_mov_b32 s7, -1
	v_lshl_add_u64 v[36:37], v[2:3], 0, s[6:7]
	v_cndmask_b32_e32 v35, v37, v35, vcc
	v_cndmask_b32_e32 v34, v36, v34, vcc
	s_nop 0
	s_mov_b64 s[6:7], 0x98
	s_waitcnt vmcnt(0)
	v_mul_f32_e32 v33, v33, v82
	v_lshl_add_u64 v[34:35], v[4:5], 0, s[6:7]
	s_movk_i32 s6, 0xf898
	s_mov_b32 s7, -1
	v_lshl_add_u64 v[36:37], v[2:3], 0, s[6:7]
	v_cndmask_b32_e32 v35, v37, v35, vcc
	v_cndmask_b32_e32 v34, v36, v34, vcc
	ds_write2_b32 v38, v0, v33 offset0:32 offset1:98
	s_nop 0
	s_mov_b64 s[6:7], 0xa0
	s_waitcnt vmcnt(0)
	v_mul_f32_e32 v0, v32, v83
	v_lshl_add_u64 v[32:33], v[4:5], 0, s[6:7]
	s_movk_i32 s6, 0xf8a0
	s_mov_b32 s7, -1
	v_lshl_add_u64 v[34:35], v[2:3], 0, s[6:7]
	v_cndmask_b32_e32 v33, v35, v33, vcc
	v_cndmask_b32_e32 v32, v34, v32, vcc
	s_nop 0
	s_mov_b64 s[6:7], 0xa8
	s_waitcnt vmcnt(0)
	v_mul_f32_e32 v31, v31, v84
	v_lshl_add_u64 v[32:33], v[4:5], 0, s[6:7]
	s_movk_i32 s6, 0xf8a8
	s_mov_b32 s7, -1
	v_lshl_add_u64 v[34:35], v[2:3], 0, s[6:7]
	v_cndmask_b32_e32 v33, v35, v33, vcc
	v_cndmask_b32_e32 v32, v34, v32, vcc
	ds_write2_b32 v38, v0, v31 offset0:164 offset1:230
	s_nop 0
	s_mov_b64 s[6:7], 0xb0
	v_add_u32_e32 v34, 0x1400, v27
	s_waitcnt vmcnt(0)
	v_mul_f32_e32 v0, v30, v85
	v_lshl_add_u64 v[30:31], v[4:5], 0, s[6:7]
	s_movk_i32 s6, 0xf8b0
	s_mov_b32 s7, -1
	v_lshl_add_u64 v[32:33], v[2:3], 0, s[6:7]
	v_cndmask_b32_e32 v31, v33, v31, vcc
	v_cndmask_b32_e32 v30, v32, v30, vcc
	s_nop 0
	s_mov_b64 s[6:7], 0xb8
	s_waitcnt vmcnt(0)
	v_mul_f32_e32 v29, v29, v86
	v_lshl_add_u64 v[30:31], v[4:5], 0, s[6:7]
	s_movk_i32 s6, 0xf8b8
	s_mov_b32 s7, -1
	v_lshl_add_u64 v[32:33], v[2:3], 0, s[6:7]
	v_cndmask_b32_e32 v31, v33, v31, vcc
	v_cndmask_b32_e32 v30, v32, v30, vcc
	ds_write2_b32 v34, v0, v29 offset0:40 offset1:106
	s_nop 0
	s_mov_b64 s[6:7], 0xc0
	s_waitcnt vmcnt(0)
	v_mul_f32_e32 v0, v28, v87
	v_lshl_add_u64 v[28:29], v[4:5], 0, s[6:7]
	s_movk_i32 s6, 0xf8c0
	s_mov_b32 s7, -1
	v_lshl_add_u64 v[30:31], v[2:3], 0, s[6:7]
	v_cndmask_b32_e32 v29, v31, v29, vcc
	v_cndmask_b32_e32 v28, v30, v28, vcc
	s_nop 0
	s_mov_b64 s[6:7], 0xc8
	s_waitcnt vmcnt(0)
	v_mul_f32_e32 v17, v17, v88
	v_lshl_add_u64 v[28:29], v[4:5], 0, s[6:7]
	s_movk_i32 s6, 0xf8c8
	s_mov_b32 s7, -1
	v_lshl_add_u64 v[30:31], v[2:3], 0, s[6:7]
	v_cndmask_b32_e32 v29, v31, v29, vcc
	v_cndmask_b32_e32 v28, v30, v28, vcc
	ds_write2_b32 v34, v0, v17 offset0:172 offset1:238
	s_nop 0
	s_mov_b64 s[6:7], 0xd0
	v_add_u32_e32 v30, 0x1800, v27
	s_waitcnt vmcnt(0)
	v_mul_f32_e32 v0, v16, v89
	v_lshl_add_u64 v[16:17], v[4:5], 0, s[6:7]
	s_movk_i32 s6, 0xf8d0
	s_mov_b32 s7, -1
	v_lshl_add_u64 v[28:29], v[2:3], 0, s[6:7]
	v_cndmask_b32_e32 v17, v29, v17, vcc
	v_cndmask_b32_e32 v16, v28, v16, vcc
	s_nop 0
	s_mov_b64 s[6:7], 0xd8
	s_waitcnt vmcnt(0)
	v_mul_f32_e32 v15, v15, v90
	v_lshl_add_u64 v[16:17], v[4:5], 0, s[6:7]
	s_movk_i32 s6, 0xf8d8
	s_mov_b32 s7, -1
	v_lshl_add_u64 v[28:29], v[2:3], 0, s[6:7]
	v_cndmask_b32_e32 v17, v29, v17, vcc
	v_cndmask_b32_e32 v16, v28, v16, vcc
	ds_write2_b32 v30, v0, v15 offset0:48 offset1:114
	s_nop 0
	s_mov_b64 s[6:7], 0xe0
	s_waitcnt vmcnt(0)
	v_mul_f32_e32 v0, v14, v91
	v_lshl_add_u64 v[14:15], v[4:5], 0, s[6:7]
	s_movk_i32 s6, 0xf8e0
	s_mov_b32 s7, -1
	v_lshl_add_u64 v[16:17], v[2:3], 0, s[6:7]
	v_cndmask_b32_e32 v15, v17, v15, vcc
	v_cndmask_b32_e32 v14, v16, v14, vcc
	s_nop 0
	s_mov_b64 s[6:7], 0xe8
	s_waitcnt vmcnt(0)
	v_mul_f32_e32 v13, v13, v92
	v_lshl_add_u64 v[14:15], v[4:5], 0, s[6:7]
	s_movk_i32 s6, 0xf8e8
	s_mov_b32 s7, -1
	v_lshl_add_u64 v[16:17], v[2:3], 0, s[6:7]
	v_cndmask_b32_e32 v15, v17, v15, vcc
	v_cndmask_b32_e32 v14, v16, v14, vcc
	ds_write2_b32 v30, v0, v13 offset0:180 offset1:246
	s_nop 0
	s_mov_b64 s[6:7], 0xf0
	s_waitcnt vmcnt(0)
	v_mul_f32_e32 v0, v12, v93
	v_lshl_add_u64 v[12:13], v[4:5], 0, s[6:7]
	s_movk_i32 s6, 0xf8f0
	s_mov_b32 s7, -1
	v_lshl_add_u64 v[14:15], v[2:3], 0, s[6:7]
	v_cndmask_b32_e32 v13, v15, v13, vcc
	v_cndmask_b32_e32 v12, v14, v12, vcc
	s_nop 0
	s_mov_b64 s[6:7], 0xf8
	v_lshl_add_u64 v[4:5], v[4:5], 0, s[6:7]
	s_movk_i32 s6, 0xf8f8
	s_mov_b32 s7, -1
	v_lshl_add_u64 v[2:3], v[2:3], 0, s[6:7]
	v_cndmask_b32_e32 v3, v3, v5, vcc
	v_cndmask_b32_e32 v2, v2, v4, vcc
	s_lshl_b32 s6, s10, 1
	s_add_u32 s6, s18, s6
	s_addc_u32 s7, s19, 0
	s_waitcnt vmcnt(0)
	v_mul_f32_e32 v11, v11, v94
	v_add_u32_e32 v12, 0x1c00, v27
	ds_write2_b32 v12, v0, v11 offset0:56 offset1:122
	s_nop 0
	s_waitcnt vmcnt(0)
	v_mul_f32_e32 v0, v10, v95
	ds_write_b32 v27, v0 offset:7920
	s_waitcnt lgkmcnt(0)
	ds_read2_b32 v[12:13], v19 offset0:33 offset1:41
	ds_read2_b32 v[14:15], v19 offset1:8
	ds_read2_b32 v[16:17], v19 offset0:66 offset1:74
	ds_read2_b32 v[28:29], v19 offset0:99 offset1:107
	ds_read2_b32 v[30:31], v19 offset0:132 offset1:140
	ds_read2_b32 v[32:33], v19 offset0:165 offset1:173
	ds_read2_b32 v[34:35], v19 offset0:198 offset1:206
	ds_read2_b32 v[36:37], v19 offset0:231 offset1:239
	v_lshlrev_b32_e32 v0, 1, v8
	v_lshl_add_u64 v[2:3], s[6:7], 0, v[0:1]
	s_mov_b64 s[6:7], 0x380000
	v_or_b32_e32 v0, s5, v18
	v_lshl_add_u64 v[10:11], v[2:3], 0, s[6:7]
	v_lshlrev_b32_e32 v0, 11, v0
	v_lshl_add_u64 v[38:39], v[10:11], 0, v[0:1]
	v_or_b32_e32 v0, s5, v20
	s_waitcnt lgkmcnt(6)
	v_cvt_pk_bf16_f32 v2, v14, v12
	s_waitcnt lgkmcnt(4)
	v_cvt_pk_bf16_f32 v3, v16, v28
	s_waitcnt lgkmcnt(2)
	v_cvt_pk_bf16_f32 v4, v30, v32
	s_waitcnt lgkmcnt(0)
	v_cvt_pk_bf16_f32 v5, v34, v36
	v_lshlrev_b32_e32 v0, 11, v0
	global_store_dwordx4 v[38:39], v[2:5], off
	s_nop 1
	v_cvt_pk_bf16_f32 v2, v15, v13
	v_cvt_pk_bf16_f32 v3, v17, v29
	v_cvt_pk_bf16_f32 v4, v31, v33
	v_cvt_pk_bf16_f32 v5, v35, v37
	v_lshl_add_u64 v[12:13], v[10:11], 0, v[0:1]
	global_store_dwordx4 v[12:13], v[2:5], off
	ds_read2_b32 v[12:13], v19 offset0:49 offset1:57
	ds_read2_b32 v[14:15], v19 offset0:16 offset1:24
	ds_read2_b32 v[16:17], v19 offset0:82 offset1:90
	ds_read2_b32 v[28:29], v19 offset0:115 offset1:123
	ds_read2_b32 v[30:31], v19 offset0:148 offset1:156
	ds_read2_b32 v[32:33], v19 offset0:181 offset1:189
	ds_read2_b32 v[34:35], v19 offset0:214 offset1:222
	ds_read2_b32 v[36:37], v19 offset0:247 offset1:255
	v_or_b32_e32 v0, s5, v21
	v_lshlrev_b32_e32 v0, 11, v0
	v_lshl_add_u64 v[38:39], v[10:11], 0, v[0:1]
	v_or_b32_e32 v0, s5, v22
	s_waitcnt lgkmcnt(6)
	v_cvt_pk_bf16_f32 v2, v14, v12
	s_waitcnt lgkmcnt(4)
	v_cvt_pk_bf16_f32 v3, v16, v28
	s_waitcnt lgkmcnt(2)
	v_cvt_pk_bf16_f32 v4, v30, v32
	s_waitcnt lgkmcnt(0)
	v_cvt_pk_bf16_f32 v5, v34, v36
	v_lshlrev_b32_e32 v0, 11, v0
	global_store_dwordx4 v[38:39], v[2:5], off
	v_lshl_add_u64 v[10:11], v[10:11], 0, v[0:1]
	s_nop 0
	v_cvt_pk_bf16_f32 v2, v15, v13
	v_cvt_pk_bf16_f32 v3, v17, v29
	v_cvt_pk_bf16_f32 v4, v31, v33
	v_cvt_pk_bf16_f32 v5, v35, v37
	global_store_dwordx4 v[10:11], v[2:5], off
	s_waitcnt lgkmcnt(0)
